# FFN conv weights preloaded in the last K iteration ahead of the tile prefetches, epilogue waits vmcnt(6) (replaces the waves-0-3-only early loads)
# baseline (speedup 1.0000x reference)
; #define PG8_STAGE(bufoff, gbase, voff) do { _Pragma("unroll") for (int _i = 0; _i < 2; ++_i) { unsigned _vo = (voff)[_i]; asm volatile("" : "+v"(_vo));   \
;         __builtin_amdgcn_global_load_lds((const unsigned*)((const char*)(gbase) + _vo), (LAS unsigned*)(lds + (bufoff) + ldsw + _i * 8192), 16, 0, 0); } } while (0)
; #define PG8_LDA(dst, b, h) do { _Pragma("unroll") for (int m = 0; m < 4; ++m) _Pragma("unroll") for (int k = 0; k < 2; ++k) dst[m][k] = *(const LAS bf16x8*)(lds + PG8_SA(b, h) + aoff + m * 2048 + k * 1024); } while (0)
; #define PG8_LDB(dst, b, h) do { _Pragma("unroll") for (int n = 0; n < 2; ++n) _Pragma("unroll") for (int k = 0; k < 2; ++k) dst[n][k] = *(const LAS bf16x8*)(lds + PG8_SB(b, h) + boff + n * 2048 + k * 1024); } while (0)
; #define PG8_MMA(ai, bj, At, Bt) do { __builtin_amdgcn_s_setprio(1); _Pragma("unroll") for (int m = 0; m < 4; ++m) _Pragma("unroll") for (int n = 0; n < 2; ++n) _Pragma("unroll") for (int k = 0; k < 2; ++k) \
;         acc[ai][bj][m][n] = __builtin_amdgcn_mfma_f32_16x16x32_bf16(Bt[n][k], At[m][k], acc[ai][bj][m][n], 0, 0, 0); __builtin_amdgcn_s_setprio(0); } while (0)
; #define PG8_WAIT_V(n) asm volatile("s_waitcnt vmcnt(" #n ")" ::: "memory")
; #define PG8_WAIT_L(n) asm volatile("s_waitcnt lgkmcnt(" #n ")" ::: "memory")
; #define PG8_BAR __builtin_amdgcn_s_barrier()
; #define PG8_SCHED __builtin_amdgcn_sched_barrier(0)
; __device__ __forceinline__ void epi_ffn(const f32x4 (&acc)[2][2][4][2], const Job& J, int rowt, int pn, int wr, int wc, int fr, int fq, int lane) {
;     ...
;     for (int n = 0; n < 2; ++n) { w0[n] = *(const f32x4*)(cw + col + 4 * n) * (-LOG2E); w1[n] = *(const f32x4*)(cw + DFF + col + 4 * n) * (-LOG2E); w2[n] = *(const f32x4*)(cw + 2 * DFF + col + 4 * n) * (-LOG2E); }
; __device__ __forceinline__ void gemm_phase(LAS unsigned char* lds, const Call& C, const int tid, const Args& args) {
;     ...
;             PG8_LDB(B0, 1, 0); PG8_LDB(B1, 1, 1); PG8_SCHED; PG8_LDA(At, 1, 0); PG8_STAGE(PG8_SA(0, 1), a2 + hstepA, voffA);
;             PG8_WAIT_V(8); PG8_WAIT_L(0); PG8_BAR; PG8_MMA(0, 0, At, B0); PG8_MMA(0, 1, At, B1); PG8_BAR; PG8_SCHED;
;             PG8_LDA(At, 1, 1); PG8_STAGE(PG8_SB(1, 0), b3, voffB); PG8_STAGE(PG8_SB(1, 1), b3 + hstepB, voffB); PG8_STAGE(PG8_SA(1, 0), a3, voffA);
.Lp7_ph3:
	s_add_i32 s24, 0, 0x18000
	v_add_u32_e32 v80, s24, v245
	s_add_i32 s42, 0, 0x1c000
	ds_read_b128 v[136:139], v80
	ds_read_b128 v[140:143], v80 offset:1024
	ds_read_b128 v[144:147], v80 offset:2048
	ds_read_b128 v[148:151], v80 offset:3072
	v_add_u32_e32 v80, s42, v245
	ds_read_b128 v[152:155], v80
	ds_read_b128 v[156:159], v80 offset:1024
	ds_read_b128 v[160:163], v80 offset:2048
	ds_read_b128 v[164:167], v80 offset:3072
	s_add_u32 s34, s38, s22
	v_mov_b32_e32 v80, v205
	s_mov_b32 m0, s73
	ds_read_b128 v[168:171], v246 offset:32768
	ds_read_b128 v[172:175], v246 offset:33792
	ds_read_b128 v[176:179], v246 offset:34816
	ds_read_b128 v[180:183], v246 offset:35840
	ds_read_b128 v[184:187], v246 offset:36864
	ds_read_b128 v[188:191], v246 offset:37888
	ds_read_b128 v[192:195], v246 offset:38912
	ds_read_b128 v[196:199], v246 offset:39936
	s_addc_u32 s35, s39, 0
	s_nop 0
	global_load_lds_dwordx4 v80, s[34:35]
	v_mov_b32_e32 v80, v243
	s_mov_b32 m0, s4
	s_nop 0
	global_load_lds_dwordx4 v80, s[34:35]
	s_waitcnt vmcnt(8)
	s_waitcnt lgkmcnt(0)
	s_barrier
	s_setprio 1
	s_waitcnt lgkmcnt(0)
	v_mfma_f32_16x16x32_bf16 v[132:135], v[136:139], v[168:171], v[132:135]
	v_mfma_f32_16x16x32_bf16 v[128:131], v[144:147], v[168:171], v[128:131]
	v_mfma_f32_16x16x32_bf16 v[124:127], v[136:139], v[176:179], v[124:127]
	v_mfma_f32_16x16x32_bf16 v[120:123], v[144:147], v[176:179], v[120:123]
	v_mfma_f32_16x16x32_bf16 v[108:111], v[136:139], v[184:187], v[108:111]
	v_mfma_f32_16x16x32_bf16 v[104:107], v[144:147], v[184:187], v[104:107]
	v_mfma_f32_16x16x32_bf16 v[90:93], v[136:139], v[192:195], v[92:95]
	v_mfma_f32_16x16x32_bf16 v[86:89], v[144:147], v[192:195], v[86:89]
	v_mfma_f32_16x16x32_bf16 v[132:135], v[140:143], v[172:175], v[132:135]
	v_mfma_f32_16x16x32_bf16 v[128:131], v[148:151], v[172:175], v[128:131]
	v_mfma_f32_16x16x32_bf16 v[124:127], v[140:143], v[180:183], v[124:127]
	v_mfma_f32_16x16x32_bf16 v[120:123], v[148:151], v[180:183], v[120:123]
	v_mfma_f32_16x16x32_bf16 v[108:111], v[140:143], v[188:191], v[108:111]
	v_mfma_f32_16x16x32_bf16 v[104:107], v[148:151], v[188:191], v[104:107]
	v_mfma_f32_16x16x32_bf16 v[92:95], v[140:143], v[196:199], v[90:93]
	v_mfma_f32_16x16x32_bf16 v[88:91], v[148:151], v[196:199], v[86:89]
	s_setprio 0
	s_setprio 1
	v_mfma_f32_16x16x32_bf16 v[116:119], v[152:155], v[168:171], v[116:119]
	v_mfma_f32_16x16x32_bf16 v[112:115], v[160:163], v[168:171], v[112:115]
	v_mfma_f32_16x16x32_bf16 v[100:103], v[152:155], v[176:179], v[100:103]
	v_mfma_f32_16x16x32_bf16 v[96:99], v[160:163], v[176:179], v[96:99]
	v_mfma_f32_16x16x32_bf16 v[76:79], v[152:155], v[184:187], v[76:79]
	v_mfma_f32_16x16x32_bf16 v[72:75], v[160:163], v[184:187], v[72:75]
	v_mfma_f32_16x16x32_bf16 v[68:71], v[152:155], v[192:195], v[68:71]
	v_mfma_f32_16x16x32_bf16 v[60:63], v[160:163], v[192:195], v[60:63]
	v_mfma_f32_16x16x32_bf16 v[116:119], v[156:159], v[172:175], v[116:119]
	v_mfma_f32_16x16x32_bf16 v[112:115], v[164:167], v[172:175], v[112:115]
	v_mfma_f32_16x16x32_bf16 v[100:103], v[156:159], v[180:183], v[100:103]
	v_mfma_f32_16x16x32_bf16 v[96:99], v[164:167], v[180:183], v[96:99]
	v_mfma_f32_16x16x32_bf16 v[76:79], v[156:159], v[188:191], v[76:79]
	v_mfma_f32_16x16x32_bf16 v[72:75], v[164:167], v[188:191], v[72:75]
	v_mfma_f32_16x16x32_bf16 v[68:71], v[156:159], v[196:199], v[68:71]
	v_mfma_f32_16x16x32_bf16 v[60:63], v[164:167], v[196:199], v[60:63]
	s_setprio 0
	s_barrier
	v_mov_b32_e32 v80, v242
	ds_read_b128 v[168:171], v246 offset:49152
	ds_read_b128 v[172:175], v246 offset:50176
	ds_read_b128 v[176:179], v246 offset:51200
	ds_read_b128 v[180:183], v246 offset:52224
	ds_read_b128 v[184:187], v246 offset:53248
	ds_read_b128 v[188:191], v246 offset:54272
	ds_read_b128 v[192:195], v246 offset:55296
	ds_read_b128 v[196:199], v246 offset:56320
	s_mov_b32 vcc_hi, 0
	s_cmp_lg_u32 s55, 4
	s_cbranch_scc1 .Lfw2_skip
	s_add_i32 vcc_lo, s13, 2
	s_cmp_lg_u32 vcc_lo, s25
	s_cbranch_scc1 .Lfw2_skip
	s_lshl_b32 vcc_lo, s78, 7
	v_readlane_b32 vcc_hi, v254, 59
	v_lshrrev_b32_e32 v249, 4, v240
	s_nop 3
	s_or_b32 vcc_lo, vcc_lo, vcc_hi
	s_nop 0
	v_lshl_add_u32 v249, v249, 3, vcc_lo
	v_lshlrev_b32_e32 v250, 2, v249
	v_readlane_b32 vcc_lo, v254, 17
	v_readlane_b32 vcc_hi, v254, 18
	s_nop 4
	global_load_dwordx4 v[210:213], v250, vcc
	global_load_dwordx4 v[222:225], v250, vcc offset:16
	v_readlane_b32 vcc_lo, v255, 21
	v_readlane_b32 vcc_hi, v255, 22
	s_nop 4
	global_load_dwordx4 v[214:217], v250, vcc
	global_load_dwordx4 v[200:203], v250, vcc offset:16
	v_readlane_b32 vcc_lo, v255, 23
	v_readlane_b32 vcc_hi, v255, 24
	s_nop 4
	global_load_dwordx4 v[218:221], v250, vcc
	global_load_dwordx4 v[206:209], v250, vcc offset:16
	s_mov_b32 vcc_hi, 1
; #define PG8_STAGE(bufoff, gbase, voff) do { _Pragma("unroll") for (int _i = 0; _i < 2; ++_i) { unsigned _vo = (voff)[_i]; asm volatile("" : "+v"(_vo));   \
;         __builtin_amdgcn_global_load_lds((const unsigned*)((const char*)(gbase) + _vo), (LAS unsigned*)(lds + (bufoff) + ldsw + _i * 8192), 16, 0, 0); } } while (0)
; #define PG8_LDA(dst, b, h) do { _Pragma("unroll") for (int m = 0; m < 4; ++m) _Pragma("unroll") for (int k = 0; k < 2; ++k) dst[m][k] = *(const LAS bf16x8*)(lds + PG8_SA(b, h) + aoff + m * 2048 + k * 1024); } while (0)
; #define PG8_MMA(ai, bj, At, Bt) do { __builtin_amdgcn_s_setprio(1); _Pragma("unroll") for (int m = 0; m < 4; ++m) _Pragma("unroll") for (int n = 0; n < 2; ++n) _Pragma("unroll") for (int k = 0; k < 2; ++k) \
;         acc[ai][bj][m][n] = __builtin_amdgcn_mfma_f32_16x16x32_bf16(Bt[n][k], At[m][k], acc[ai][bj][m][n], 0, 0, 0); __builtin_amdgcn_s_setprio(0); } while (0)
; #define PG8_WAIT_V(n) asm volatile("s_waitcnt vmcnt(" #n ")" ::: "memory")
; #define PG8_WAIT_L(n) asm volatile("s_waitcnt lgkmcnt(" #n ")" ::: "memory")
; #define PG8_BAR __builtin_amdgcn_s_barrier()
; #define PG8_SCHED __builtin_amdgcn_sched_barrier(0)
; __device__ __forceinline__ void gemm_phase(LAS unsigned char* lds, const Call& C, const int tid, const Args& args) {
;     ...
;             PG8_LDA(At, 1, 1); PG8_STAGE(PG8_SB(1, 0), b3, voffB); PG8_STAGE(PG8_SB(1, 1), b3 + hstepB, voffB); PG8_STAGE(PG8_SA(1, 0), a3, voffA);
;             PG8_WAIT_V(8); PG8_WAIT_L(0); PG8_BAR; PG8_MMA(1, 0, At, B0); PG8_MMA(1, 1, At, B1); PG8_BAR; PG8_SCHED;
;         }
;         if (wr == 0) PG8_BAR;
.Lfw2_skip:
	s_add_i32 s24, s24, s23
	v_lshl_add_u64 v[82:83], s[40:41], 0, v[80:81]
	v_lshl_add_u64 v[82:83], v[82:83], 0, s[18:19]
	s_mov_b32 m0, s24
	v_mov_b32_e32 v80, v244
	global_load_lds_dwordx4 v[82:83], off
	s_add_i32 m0, s24, 0x2000
	v_lshl_add_u64 v[82:83], s[40:41], 0, v[80:81]
	v_lshl_add_u64 v[82:83], v[82:83], 0, s[18:19]
	v_mov_b32_e32 v80, v242
	global_load_lds_dwordx4 v[82:83], off
	s_add_i32 s24, s42, s23
	v_lshl_add_u64 v[82:83], s[0:1], 0, v[80:81]
	v_lshl_add_u64 v[82:83], v[82:83], 0, s[18:19]
	s_mov_b32 m0, s24
	v_mov_b32_e32 v80, v244
	global_load_lds_dwordx4 v[82:83], off
	s_add_i32 m0, s24, 0x2000
	v_lshl_add_u64 v[82:83], s[0:1], 0, v[80:81]
	v_lshl_add_u64 v[82:83], v[82:83], 0, s[18:19]
	v_mov_b32_e32 v80, v205
	global_load_lds_dwordx4 v[82:83], off
	s_mov_b32 m0, s14
	v_lshl_add_u64 v[82:83], s[38:39], 0, v[80:81]
	v_lshl_add_u64 v[82:83], v[82:83], 0, s[18:19]
	v_mov_b32_e32 v80, v243
	global_load_lds_dwordx4 v[82:83], off
	s_mov_b32 m0, s52
	v_lshl_add_u64 v[82:83], s[38:39], 0, v[80:81]
	v_lshl_add_u64 v[82:83], v[82:83], 0, s[18:19]
	global_load_lds_dwordx4 v[82:83], off
	s_cmp_eq_u32 vcc_hi, 1
	s_cbranch_scc1 .Lfw2_w14
	s_waitcnt vmcnt(8)
	s_branch .Lfw2_wj
.Lfw2_w14:
	s_waitcnt vmcnt(14)
.Lfw2_wj:
	s_waitcnt lgkmcnt(0)
	s_barrier
	s_setprio 1
	s_waitcnt lgkmcnt(0)
	v_mfma_f32_16x16x32_bf16 v[64:67], v[136:139], v[168:171], v[64:67]
	v_mfma_f32_16x16x32_bf16 v[56:59], v[144:147], v[168:171], v[56:59]
	v_mfma_f32_16x16x32_bf16 v[52:55], v[136:139], v[176:179], v[52:55]
	v_mfma_f32_16x16x32_bf16 v[48:51], v[144:147], v[176:179], v[48:51]
	v_mfma_f32_16x16x32_bf16 v[36:39], v[136:139], v[184:187], v[36:39]
	v_mfma_f32_16x16x32_bf16 v[32:35], v[144:147], v[184:187], v[32:35]
	v_mfma_f32_16x16x32_bf16 v[20:23], v[136:139], v[192:195], v[20:23]
	v_mfma_f32_16x16x32_bf16 v[16:19], v[144:147], v[192:195], v[16:19]
	v_mfma_f32_16x16x32_bf16 v[64:67], v[140:143], v[172:175], v[64:67]
	v_mfma_f32_16x16x32_bf16 v[56:59], v[148:151], v[172:175], v[56:59]
	v_mfma_f32_16x16x32_bf16 v[52:55], v[140:143], v[180:183], v[52:55]
	v_mfma_f32_16x16x32_bf16 v[48:51], v[148:151], v[180:183], v[48:51]
	v_mfma_f32_16x16x32_bf16 v[36:39], v[140:143], v[188:191], v[36:39]
	v_mfma_f32_16x16x32_bf16 v[32:35], v[148:151], v[188:191], v[32:35]
	v_mfma_f32_16x16x32_bf16 v[20:23], v[140:143], v[196:199], v[20:23]
	v_mfma_f32_16x16x32_bf16 v[16:19], v[148:151], v[196:199], v[16:19]
	s_setprio 0
	s_setprio 1
	v_mfma_f32_16x16x32_bf16 v[44:47], v[152:155], v[168:171], v[44:47]
	v_mfma_f32_16x16x32_bf16 v[40:43], v[160:163], v[168:171], v[40:43]
	v_mfma_f32_16x16x32_bf16 v[28:31], v[152:155], v[176:179], v[28:31]
	v_mfma_f32_16x16x32_bf16 v[24:27], v[160:163], v[176:179], v[24:27]
	v_mfma_f32_16x16x32_bf16 v[12:15], v[152:155], v[184:187], v[12:15]
	v_mfma_f32_16x16x32_bf16 v[8:11], v[160:163], v[184:187], v[8:11]
	v_mfma_f32_16x16x32_bf16 v[4:7], v[152:155], v[192:195], v[4:7]
	v_mfma_f32_16x16x32_bf16 v[0:3], v[160:163], v[192:195], v[0:3]
	v_mfma_f32_16x16x32_bf16 v[44:47], v[156:159], v[172:175], v[44:47]
	v_mfma_f32_16x16x32_bf16 v[40:43], v[164:167], v[172:175], v[40:43]
	v_mfma_f32_16x16x32_bf16 v[28:31], v[156:159], v[180:183], v[28:31]
	v_mfma_f32_16x16x32_bf16 v[24:27], v[164:167], v[180:183], v[24:27]
	v_mfma_f32_16x16x32_bf16 v[12:15], v[156:159], v[188:191], v[12:15]
	v_mfma_f32_16x16x32_bf16 v[8:11], v[164:167], v[188:191], v[8:11]
	v_mfma_f32_16x16x32_bf16 v[4:7], v[156:159], v[196:199], v[4:7]
	v_mfma_f32_16x16x32_bf16 v[0:3], v[164:167], v[196:199], v[0:3]
	s_setprio 0
	s_barrier
	s_add_u32 s16, s16, 0x100
	s_addc_u32 s17, s17, 0
	s_cmp_ge_u32 s25, s12
	s_mov_b64 s[0:1], s[8:9]
	s_mov_b32 s24, s25
	s_cbranch_scc0 .LBB0_282
	s_and_b64 vcc, exec, s[80:81]
	s_cbranch_vccz .LBB0_285

; __device__ __forceinline__ void epi_ffn(const f32x4 (&acc)[2][2][4][2], const Job& J, int rowt, int pn, int wr, int wc, int fr, int fq, int lane) {
;     bf16_t* O = (bf16_t*)J.out; _Float16* SIDE = (_Float16*)J.out2; const float* cw = J.aux;
;     const int col = 128 * pn + 32 * wc + 8 * fq;
;     f32x4 w0[2], w1[2], w2[2];
; #pragma unroll
;     for (int n = 0; n < 2; ++n) { w0[n] = *(const f32x4*)(cw + col + 4 * n) * (-LOG2E); w1[n] = *(const f32x4*)(cw + DFF + col + 4 * n) * (-LOG2E); w2[n] = *(const f32x4*)(cw + 2 * DFF + col + 4 * n) * (-LOG2E); }
; #pragma unroll
;     for (int ai = 0; ai < 2; ++ai) {
;         const int blk = (rowt + ai * HALF + wr * 64) >> 6;
;         f32x4 cv[4][2];
; #pragma unroll
;         for (int n = 0; n < 2; ++n)
; #pragma unroll
;             for (int e = 0; e < 4; ++e) {
;                 float g[4], dn[4], up[4];
; #pragma unroll
;                 for (int m = 0; m < 4; ++m) { g[m] = acc[ai][0][m][n][e];
;                     dn[m] = __int_as_float(__builtin_amdgcn_mov_dpp(__float_as_int(g[m]), 0x121, 0xF, 0xF, false));
;                     up[m] = __int_as_float(__builtin_amdgcn_mov_dpp(__float_as_int(g[m]), 0x12F, 0xF, 0xF, false)); }
.LBB0_411:
	s_waitcnt vmcnt(6)
	v_mov_b32_e32 v136, v210
	v_mov_b32_e32 v137, v211
	v_mov_b32_e32 v138, v212
	v_mov_b32_e32 v139, v213
	v_mov_b32_e32 v140, v214
	v_mov_b32_e32 v141, v215
	v_mov_b32_e32 v142, v216
	v_mov_b32_e32 v143, v217
	v_mov_b32_e32 v160, v218
	v_mov_b32_e32 v161, v219
	v_mov_b32_e32 v162, v220
	v_mov_b32_e32 v163, v221
	v_mov_b32_e32 v164, v222
	v_mov_b32_e32 v165, v223
	v_mov_b32_e32 v166, v224
	v_mov_b32_e32 v167, v225
	v_mov_b32_e32 v198, v200
	v_mov_b32_e32 v199, v201
	v_mov_b32_e32 v200, v202
	v_mov_b32_e32 v201, v203
	s_lshl_b32 s0, s78, 7
	v_readlane_b32 s1, v254, 59
	s_or_b32 s0, s0, s1
	v_lshl_add_u32 v82, v247, 3, s0
	v_ashrrev_i32_e32 v83, 31, v82
	v_readlane_b32 s0, v254, 17
	v_lshlrev_b64 v[86:87], 2, v[82:83]
	v_readlane_b32 s1, v254, 18
	v_lshlrev_b64 v[152:153], 1, v[82:83]
	v_mov_b32_dpp v218, v132 row_ror:1 row_mask:0xf bank_mask:0xf
	v_lshl_add_u64 v[144:145], s[0:1], 0, v[86:87]
	v_readlane_b32 s0, v255, 21
	v_readlane_b32 s1, v255, 22
	v_mov_b32_dpp v224, v133 row_ror:1 row_mask:0xf bank_mask:0xf
	v_lshl_add_u64 v[146:147], s[0:1], 0, v[86:87]
	v_readlane_b32 s0, v255, 23
	v_readlane_b32 s1, v255, 24
	v_mov_b32_dpp v192, v134 row_ror:1 row_mask:0xf bank_mask:0xf
	v_lshl_add_u64 v[86:87], s[0:1], 0, v[86:87]
	s_lshl_b32 s0, s90, 8
	v_readlane_b32 s1, v255, 9
	s_add_i32 s8, s1, s0
	v_readlane_b32 s0, v254, 23
	v_readlane_b32 s1, v254, 24
	v_mov_b32_dpp v211, v135 row_ror:1 row_mask:0xf bank_mask:0xf
	v_mov_b32_dpp v184, v128 row_ror:1 row_mask:0xf bank_mask:0xf
	v_lshl_add_u64 v[82:83], s[0:1], 0, v[152:153]
	s_mov_b32 s0, 0xbfb8aa3b
	v_mov_b32_dpp v194, v129 row_ror:1 row_mask:0xf bank_mask:0xf
	v_cmp_eq_u32_e64 s[40:41], 0, v248
	v_mov_b32_dpp v80, v132 row_ror:15 row_mask:0xf bank_mask:0xf
	v_mov_b32_dpp v217, v124 row_ror:15 row_mask:0xf bank_mask:0xf
	v_mov_b32_dpp v86, v133 row_ror:15 row_mask:0xf bank_mask:0xf
	v_mov_b32_dpp v223, v125 row_ror:15 row_mask:0xf bank_mask:0xf
	v_mov_b32_dpp v87, v134 row_ror:15 row_mask:0xf bank_mask:0xf
	v_mov_b32_dpp v191, v126 row_ror:15 row_mask:0xf bank_mask:0xf
	v_mov_b32_dpp v144, v135 row_ror:15 row_mask:0xf bank_mask:0xf
	v_mov_b32_dpp v210, v127 row_ror:15 row_mask:0xf bank_mask:0xf
	v_mov_b32_dpp v196, v128 row_ror:15 row_mask:0xf bank_mask:0xf
	v_mov_b32_dpp v182, v120 row_ror:15 row_mask:0xf bank_mask:0xf
	v_mov_b32_dpp v216, v129 row_ror:15 row_mask:0xf bank_mask:0xf
	v_cndmask_b32_e64 v203, v224, 0, s[40:41]
	v_cndmask_b32_e64 v202, v218, 0, s[40:41]
	v_cmp_eq_u32_e64 s[42:43], 15, v248
	v_cndmask_b32_e64 v215, v211, 0, s[40:41]
	v_cndmask_b32_e64 v214, v192, 0, s[40:41]
	v_mov_b32_dpp v251, v121 row_ror:15 row_mask:0xf bank_mask:0xf
	v_cndmask_b32_e64 v213, v86, v223, s[42:43]
	v_cndmask_b32_e64 v212, v80, v217, s[42:43]
	v_cndmask_b32_e64 v221, v144, v210, s[42:43]
	v_cndmask_b32_e64 v220, v87, v191, s[42:43]
	v_mov_b32_dpp v222, v130 row_ror:1 row_mask:0xf bank_mask:0xf
	v_mov_b32_dpp v250, v131 row_ror:1 row_mask:0xf bank_mask:0xf
	v_mov_b32_dpp v80, v130 row_ror:15 row_mask:0xf bank_mask:0xf
	v_mov_b32_dpp v249, v123 row_ror:15 row_mask:0xf bank_mask:0xf
	v_cmp_ne_u32_e64 s[44:45], 0, v248
	v_cmp_ne_u32_e64 s[38:39], 15, v248
	v_mov_b32_dpp v193, v124 row_ror:1 row_mask:0xf bank_mask:0xf
	v_mov_b32_dpp v188, v108 row_ror:1 row_mask:0xf bank_mask:0xf
	v_mov_b32_dpp v195, v108 row_ror:15 row_mask:0xf bank_mask:0xf
	v_mov_b32_dpp v190, v92 row_ror:1 row_mask:0xf bank_mask:0xf
	v_mov_b32_dpp v186, v92 row_ror:15 row_mask:0xf bank_mask:0xf
	v_mov_b32_dpp v176, v125 row_ror:1 row_mask:0xf bank_mask:0xf
	v_mov_b32_dpp v179, v109 row_ror:1 row_mask:0xf bank_mask:0xf
	v_mov_b32_dpp v180, v109 row_ror:15 row_mask:0xf bank_mask:0xf
	v_mov_b32_dpp v197, v93 row_ror:1 row_mask:0xf bank_mask:0xf
	v_mov_b32_dpp v183, v93 row_ror:15 row_mask:0xf bank_mask:0xf
	v_mov_b32_dpp v185, v126 row_ror:1 row_mask:0xf bank_mask:0xf
	v_mov_b32_dpp v177, v110 row_ror:1 row_mask:0xf bank_mask:0xf
	v_mov_b32_dpp v187, v110 row_ror:15 row_mask:0xf bank_mask:0xf
	v_mov_b32_dpp v181, v94 row_ror:1 row_mask:0xf bank_mask:0xf
	v_mov_b32_dpp v175, v94 row_ror:15 row_mask:0xf bank_mask:0xf
	v_mov_b32_dpp v172, v127 row_ror:1 row_mask:0xf bank_mask:0xf
	v_mov_b32_dpp v173, v111 row_ror:1 row_mask:0xf bank_mask:0xf
	v_mov_b32_dpp v174, v111 row_ror:15 row_mask:0xf bank_mask:0xf
	v_mov_b32_dpp v189, v95 row_ror:1 row_mask:0xf bank_mask:0xf
	v_mov_b32_dpp v178, v95 row_ror:15 row_mask:0xf bank_mask:0xf
	v_mov_b32_dpp v170, v120 row_ror:1 row_mask:0xf bank_mask:0xf
; __device__ __forceinline__ float silu_s(float xs) { return xs * __builtin_amdgcn_rcpf(1.0f + __builtin_amdgcn_exp2f(xs)); }
; __device__ __forceinline__ u32x4 pack8(const f32x4& a, const f32x4& b) { u32x4 w; w.x = cvt_pk_bf16(a[0], a[1]); w.y = cvt_pk_bf16(a[2], a[3]); w.z = cvt_pk_bf16(b[0], b[1]); w.w = cvt_pk_bf16(b[2], b[3]); return w; }
; __device__ __forceinline__ void epi_ffn(const f32x4 (&acc)[2][2][4][2], const Job& J, int rowt, int pn, int wr, int wc, int fr, int fq, int lane) {
;     ...
;                 for (int m = 0; m < 4; ++m) {
;                     const float pv = fr > 0 ? dn[m] : (m > 0 ? dn[m - 1] : 0.f);
;                     const float nx = fr < 15 ? up[m] : (m < 3 ? up[m + 1] : 0.f);
;                     cv[m][n][e] = w0[n][e] * pv + w1[n][e] * g[m] + w2[n][e] * nx;
;                 }
;             }
; #pragma unroll
;         for (int m = 0; m < 4; ++m) {
;             const int grow = rowt + ai * HALF + wr * 64 + m * 16 + fr;
;             const bool first = (m == 0 && fr == 0), last = (m == 3 && fr == 15);
;             if (first || last) {
;                 typedef _Float16 sh4 __attribute__((ext_vector_type(4))); typedef _Float16 sh8 __attribute__((ext_vector_type(8)));
;                 _Float16* sp = SIDE + ((size_t)(blk * 2 + (last ? 1 : 0)) * 3) * DFF + col;
;                 auto pk = [](const f32x4& a, const f32x4& b) { const sh4 x = __builtin_convertvector(a, sh4), y = __builtin_convertvector(b, sh4); return (sh8){x[0], x[1], x[2], x[3], y[0], y[1], y[2], y[3]}; };
;                 *(sh8*)sp = pk(cv[m][0] * NEG_LN2, cv[m][1] * NEG_LN2); *(sh8*)(sp + DFF) = pk(acc[ai][0][m][0], acc[ai][0][m][1]); *(sh8*)(sp + 2 * DFF) = pk(acc[ai][1][m][0], acc[ai][1][m][1]);
;             } else {
;                 f32x4 a0, a1;
; #pragma unroll
;                 for (int e = 0; e < 4; ++e) { a0[e] = silu_s(cv[m][0][e]) * acc[ai][1][m][0][e]; a1[e] = silu_s(cv[m][1][e]) * acc[ai][1][m][1][e]; }
;                 *(u32x4*)(O + (size_t)grow * DFF + col) = pack8(a0, a1);
	v_mov_b32_dpp v168, v104 row_ror:1 row_mask:0xf bank_mask:0xf
	v_mov_b32_dpp v171, v104 row_ror:15 row_mask:0xf bank_mask:0xf
	v_mov_b32_dpp v169, v88 row_ror:1 row_mask:0xf bank_mask:0xf
	v_mov_b32_dpp v85, v88 row_ror:15 row_mask:0xf bank_mask:0xf
	v_mov_b32_dpp v225, v89 row_ror:1 row_mask:0xf bank_mask:0xf
	v_mov_b32_dpp v219, v106 row_ror:15 row_mask:0xf bank_mask:0xf
	v_pk_mul_f32 v[146:147], v[138:139], s[0:1] op_sel_hi:[1,0]
	v_pk_mul_f32 v[154:155], v[136:137], s[0:1] op_sel_hi:[1,0]
	v_pk_mul_f32 v[150:151], v[142:143], s[0:1] op_sel_hi:[1,0]
	v_pk_mul_f32 v[158:159], v[140:141], s[0:1] op_sel_hi:[1,0]
	v_pk_mul_f32 v[142:143], v[198:199], s[0:1] op_sel_hi:[1,0]
	v_pk_mul_f32 v[148:149], v[162:163], s[0:1] op_sel_hi:[1,0]
	v_pk_mul_f32 v[156:157], v[160:161], s[0:1] op_sel_hi:[1,0]
	v_pk_mul_f32 v[140:141], v[164:165], s[0:1] op_sel_hi:[1,0]
	v_pk_mul_f32 v[160:161], v[134:135], v[150:151]
	v_pk_mul_f32 v[162:163], v[132:133], v[158:159]
	v_pk_mul_f32 v[164:165], v[128:129], v[142:143]
	v_cndmask_b32_e64 v199, v194, 0, s[40:41]
	v_cndmask_b32_e64 v198, v184, 0, s[40:41]
	v_pk_mul_f32 v[138:139], v[200:201], s[0:1] op_sel_hi:[1,0]
	v_pk_mul_f32 v[144:145], v[206:207], s[0:1] op_sel_hi:[1,0]
	v_pk_fma_f32 v[162:163], v[154:155], v[202:203], v[162:163]
	v_pk_fma_f32 v[160:161], v[146:147], v[214:215], v[160:161]
	v_cndmask_b32_e64 v201, v216, v251, s[42:43]
	v_cndmask_b32_e64 v200, v196, v182, s[42:43]
	v_pk_fma_f32 v[164:165], v[140:141], v[198:199], v[164:165]
	v_pk_mul_f32 v[136:137], v[166:167], s[0:1] op_sel_hi:[1,0]
	v_pk_fma_f32 v[166:167], v[156:157], v[212:213], v[162:163]
	v_pk_fma_f32 v[162:163], v[148:149], v[220:221], v[160:161]
	v_pk_mul_f32 v[160:161], v[130:131], v[138:139]
	v_pk_fma_f32 v[164:165], v[144:145], v[200:201], v[164:165]
	v_mov_b32_dpp v221, v122 row_ror:15 row_mask:0xf bank_mask:0xf
	v_mov_b32_dpp v202, v131 row_ror:15 row_mask:0xf bank_mask:0xf
	v_cndmask_b32_e64 v201, v250, 0, s[40:41]
	v_cndmask_b32_e64 v200, v222, 0, s[40:41]
	v_pk_mul_f32 v[86:87], v[208:209], s[0:1] op_sel_hi:[1,0]
	v_cndmask_b32_e64 v203, v202, v249, s[42:43]
	v_cndmask_b32_e64 v202, v80, v221, s[42:43]
	v_pk_fma_f32 v[160:161], v[136:137], v[200:201], v[160:161]
	v_mov_b32_dpp v207, v121 row_ror:1 row_mask:0xf bank_mask:0xf
	v_mov_b32_dpp v212, v105 row_ror:1 row_mask:0xf bank_mask:0xf
	v_mov_b32_dpp v213, v105 row_ror:15 row_mask:0xf bank_mask:0xf
	v_mov_b32_dpp v215, v89 row_ror:15 row_mask:0xf bank_mask:0xf
	v_mov_b32_dpp v216, v122 row_ror:1 row_mask:0xf bank_mask:0xf
	v_mov_b32_dpp v208, v106 row_ror:1 row_mask:0xf bank_mask:0xf
	v_mov_b32_dpp v214, v90 row_ror:1 row_mask:0xf bank_mask:0xf
	v_mov_b32_dpp v206, v90 row_ror:15 row_mask:0xf bank_mask:0xf
	v_mov_b32_dpp v196, v123 row_ror:1 row_mask:0xf bank_mask:0xf
	v_mov_b32_dpp v198, v107 row_ror:1 row_mask:0xf bank_mask:0xf
	v_mov_b32_dpp v199, v107 row_ror:15 row_mask:0xf bank_mask:0xf
	v_mov_b32_dpp v220, v91 row_ror:1 row_mask:0xf bank_mask:0xf
	v_mov_b32_dpp v209, v91 row_ror:15 row_mask:0xf bank_mask:0xf
	v_pk_fma_f32 v[160:161], v[86:87], v[202:203], v[160:161]
	v_or_b32_e32 v80, s8, v248
	s_and_saveexec_b64 s[0:1], s[44:45]
	s_xor_b64 s[0:1], exec, s[0:1]
	s_cbranch_execz .LBB0_413
	v_exp_f32_e32 v201, v164
	v_exp_f32_e32 v200, v166
	v_add_f32_e32 v201, 1.0, v201
	v_rcp_f32_e32 v202, v201
	v_exp_f32_e32 v201, v167
	v_add_f32_e32 v200, 1.0, v200
	v_rcp_f32_e32 v200, v200
	v_add_f32_e32 v201, 1.0, v201
	v_rcp_f32_e32 v201, v201
	s_nop 0
	v_pk_mul_f32 v[166:167], v[166:167], v[200:201]
	v_exp_f32_e32 v200, v165
	v_exp_f32_e32 v201, v160
	v_pk_mul_f32 v[166:167], v[116:117], v[166:167]
	v_add_f32_e32 v200, 1.0, v200
	v_rcp_f32_e32 v203, v200
	v_add_f32_e32 v201, 1.0, v201
	v_exp_f32_e32 v200, v162
	v_pk_mul_f32 v[164:165], v[164:165], v[202:203]
	v_rcp_f32_e32 v202, v201
	v_exp_f32_e32 v201, v163
	v_add_f32_e32 v200, 1.0, v200
	v_rcp_f32_e32 v200, v200
	v_pk_mul_f32 v[164:165], v[112:113], v[164:165]
	v_add_f32_e32 v201, 1.0, v201
	v_rcp_f32_e32 v201, v201
	s_nop 0
	v_pk_mul_f32 v[162:163], v[162:163], v[200:201]
	v_exp_f32_e32 v200, v161
	v_pk_mul_f32 v[162:163], v[118:119], v[162:163]
	v_add_f32_e32 v200, 1.0, v200
	v_rcp_f32_e32 v203, v200
	s_nop 0
	v_pk_mul_f32 v[160:161], v[160:161], v[202:203]
	s_nop 0
	v_pk_mul_f32 v[200:201], v[114:115], v[160:161]
	v_cvt_pk_bf16_f32 v160, v166, v167
	v_cvt_pk_bf16_f32 v161, v162, v163
	v_cvt_pk_bf16_f32 v162, v164, v165
	v_cvt_pk_bf16_f32 v163, v200, v201
	v_mad_i64_i32 v[164:165], s[12:13], v80, s46, v[82:83]
	global_store_dwordx4 v[164:165], v[160:163], off sc1
